# w_in GEMM: layer 0 one tile group per XCD rotated by 12 positions per XCD with the context-row tiles as the split round; layer 1 198 per XCD with 12 positions of stagger
# speedup vs baseline: 1.0022x; 1.0022x over previous
.Lgi_sk_rm0:
	s_and_b32 s0, s57, 7
	s_lshr_b32 s1, s57, 3
	s_mul_i32 s57, s0, 12
	s_add_u32 s1, s1, s57
	s_cmpk_ge_u32 s1, 192
	s_cselect_b32 s57, 192, 0
	s_sub_u32 s1, s1, s57
	s_mul_i32 s0, s0, 192
	s_add_u32 s57, s0, s1
	s_branch .Lgi_sk_inv

.Lgi_sk_rm:
	s_and_b32 s0, s57, 7
	s_lshr_b32 s1, s57, 3
	s_cmpk_ge_u32 s1, 192
	s_cbranch_scc1 .Lgi_sk_nr
	s_mul_i32 s57, s0, 6
	s_add_u32 s1, s1, s57
	s_cmpk_ge_u32 s1, 192
	s_cselect_b32 s57, 192, 0
	s_sub_u32 s1, s1, s57
